# row-block seams: four-workgroup rendezvous per 256-row block replaces the XCD-wide seam at the six chain seams (rows of norm_rows / diff_final remapped to the block)
# speedup vs baseline: 1.0080x; 1.0080x over previous
; #define LAS __attribute__((address_space(3)))
; __device__ __forceinline__ unsigned xb_add(unsigned* p, unsigned v) { return __hip_atomic_fetch_add(p, v, __ATOMIC_RELAXED, __HIP_MEMORY_SCOPE_AGENT); }
; __device__ __forceinline__ unsigned xb_xcc_id() { return (unsigned)__builtin_amdgcn_s_getreg((3 << 11) | 20) & 0xFu; }
; __device__ __forceinline__ XcdBarrier xcd_barrier_post(unsigned* bar, volatile LAS unsigned* st) {
;     XcdBarrier b; b.bar = bar; b.x = xb_xcc_id(); b.st = st;
;     if (threadIdx.x == 0) (void)xb_add(&bar[XB_XCNT(b.x)], 1u);
;     return b;
; __global__ void __launch_bounds__(NTHR, 2) fwd(Args args) {
;     ...
;     const int lo = args.ph_lo, hi = args.ph_hi;
;     if (threadIdx.x < 64) MISC[threadIdx.x] = 0;
;     __syncthreads();
;     XcdBarrier bar = xcd_barrier_post(ctl + CW_BAR, (volatile LAS unsigned*)(MISC + 8));
_Z3fwd4Args:
	s_mov_b32 s100, 0
	s_mov_b32 s101, 0
	s_mov_b32 s98, 0
	s_mov_b32 s99, 0
	s_load_dwordx2 s[58:59], s[0:1], 0xb0
	s_load_dword s3, s[0:1], 0xb8
	s_add_u32 s4, s0, 0xb8
	s_addc_u32 s5, s1, 0
	v_and_b32_e32 v232, 0x3ff, v0
	v_writelane_b32 v254, s4, 0
	v_cmp_gt_u32_e32 vcc, 64, v232
	s_nop 0
	v_writelane_b32 v254, s5, 1
	s_and_saveexec_b64 s[4:5], vcc
	v_lshl_add_u32 v1, v232, 2, 0
	v_add_u32_e32 v1, 0x22000, v1
	v_mov_b32_e32 v2, 0
	ds_write_b32 v1, v2
	s_or_b64 exec, exec, s[4:5]
	s_mov_b32 s4, 21
	s_waitcnt lgkmcnt(0)
	s_barrier
	s_ashr_i32 s5, s4, 31
	s_lshl_b64 s[4:5], s[4:5], 3
	s_add_u32 s4, s0, s4
	s_addc_u32 s5, s1, s5
	s_load_dwordx2 s[8:9], s[4:5], 0x0
	s_getreg_b32 s4, hwreg(HW_REG_XCC_ID, 0, 4)
	v_cmp_eq_u32_e64 s[74:75], 0, v232
	s_waitcnt lgkmcnt(0)
	s_add_u32 s10, s8, 0x8000
	s_addc_u32 s11, s9, 0
	s_and_b32 s52, s4, 15
	s_and_saveexec_b64 s[4:5], s[74:75]
	s_cbranch_execz .LBB0_5
	s_mov_b64 s[6:7], exec
	v_mbcnt_lo_u32_b32 v1, s6, 0
	v_mbcnt_hi_u32_b32 v1, s7, v1
	v_cmp_eq_u32_e32 vcc, 0, v1
	s_and_b64 s[12:13], exec, vcc
	s_mov_b64 exec, s[12:13]
	s_cbranch_execz .LBB0_5
	s_lshl_b32 s12, s52, 8
	s_bcnt1_i32_b64 s6, s[6:7]
	v_mov_b32_e32 v1, s12
	v_mov_b32_e32 v2, s6
	global_atomic_add v1, v2, s[10:11] offset:1024
	s_and_b32 s12, s2, 7
	s_lshl_b32 s12, s12, 6
	s_addk_i32 s12, 0x3800
	s_lshl_b32 s13, 1, s52
	v_mov_b32_e32 v3, s12
	v_mov_b32_e32 v4, s13
	global_atomic_or v3, v4, s[10:11]

; __device__ __forceinline__ const float* karg(int k) { int kk = k; asm volatile("" : "+s"(kk)); return ((const float* const __attribute__((address_space(4)))*)__builtin_amdgcn_kernarg_segment_ptr())[kk]; }
; #define PIN_TID() int tid = threadIdx.x; asm volatile("" : "+v"(tid)); const int lane = tid & 63, wid = __builtin_amdgcn_readfirstlane(tid >> 6), gw = blockIdx.x * NWAVES + wid; (void)lane; (void)gw
; #define lambda_init (0.8f - 0.6f * expf(-0.3f * (float)l))
; __device__ __forceinline__ void diff_final(const bfu* D0, const bfu* D1, float lam, const float* sg, float omli, bfu* CAT, int gw, int NGW, int lane) {
;     const int half = lane >> 5, l32 = lane & 31;
;     for (int it = gw * 2 + half; it < M * 6; it += NGW * 2) { const int row = it / 6, h = it - row * 6;
; __global__ void __launch_bounds__(NTHR, 2) fwd(Args args) {
;     ...
;         if (XEN(4) && IN_PH()) for (int rep = 0; rep < XREP(4); ++rep) { PIN_TID();
;             float lam;
;             { const float a = (lane < 64) ? karg(4)[l * 64 + lane] * karg(5)[l * 64 + lane] : 0.f, b_ = karg(6)[l * 64 + lane] * karg(7)[l * 64 + lane];
;               lam = expf(wave_sum(a)) - expf(wave_sum(b_)) + lambda_init; lam = __builtin_bit_cast(float, __builtin_amdgcn_readfirstlane(__builtin_bit_cast(int, lam))); }
;             diff_final(DIFF, DIFF1, lam, karg(8) + l * 768, 1.f - lambda_init, CAT, gw, NGW, lane);
.LBB0_498:
	s_cmp_le_i32 s58, s20
	s_cselect_b64 s[4:5], -1, 0
	s_and_b64 s[22:23], s[4:5], s[26:27]
	s_andn2_b64 vcc, exec, s[22:23]
	s_cbranch_vccnz .LBB0_503
	v_readlane_b32 s35, v255, 30
	s_mov_b32 s26, 0x3fb8aa3b
	s_mov_b32 s22, 4
	v_cvt_f32_u32_e32 v0, s35
	s_mov_b32 s27, 0xc2ce8ed0
	s_mov_b32 s34, 0x42b17218
	v_mov_b32_e32 v18, 0x7f800000
	v_mul_f32_e32 v0, 0xbe99999a, v0
	v_mul_f32_e32 v2, 0x3fb8aa3b, v0
	v_fma_f32 v3, v0, s26, -v2
	v_rndne_f32_e32 v4, v2
	v_fmac_f32_e32 v3, 0x32a5705f, v0
	v_sub_f32_e32 v2, v2, v4
	v_add_f32_e32 v2, v2, v3
	v_cvt_i32_f32_e32 v3, v4
	v_mov_b32_e32 v4, v232
	v_exp_f32_e32 v2, v2
	s_ashr_i32 s23, s22, 31
	s_lshl_b64 s[22:23], s[22:23], 3
	s_add_u32 s22, s0, s22
	s_addc_u32 s23, s1, s23
	v_ldexp_f32 v2, v2, v3
	v_cmp_ngt_f32_e32 vcc, s27, v0
	s_load_dwordx2 s[22:23], s[22:23], 0x0
	v_and_b32_e32 v3, 63, v4
	v_cndmask_b32_e32 v2, 0, v2, vcc
	v_cmp_nlt_f32_e32 vcc, s34, v0
	v_mov_b32_e32 v0, 0x3f4ccccd
	v_and_b32_e32 v5, 64, v240
	v_cndmask_b32_e32 v2, v18, v2, vcc
	v_fmamk_f32 v10, v2, 0xbf19999a, v0
	v_lshl_or_b32 v0, s35, 6, v3
	v_lshlrev_b64 v[6:7], 2, v[0:1]
	s_waitcnt lgkmcnt(0)
	v_lshl_add_u64 v[8:9], s[22:23], 0, v[6:7]
	s_mov_b32 s22, 5
	global_load_dword v0, v[8:9], off
	s_ashr_i32 s23, s22, 31
	s_lshl_b64 s[22:23], s[22:23], 3
	s_add_u32 s22, s0, s22
	s_addc_u32 s23, s1, s23
	s_load_dwordx2 s[22:23], s[22:23], 0x0
	v_add_u32_e32 v16, 64, v5
	v_xor_b32_e32 v5, 1, v240
	v_cmp_lt_i32_e32 vcc, v5, v16
	v_readfirstlane_b32 s20, v4
	s_waitcnt lgkmcnt(0)
	v_lshl_add_u64 v[8:9], s[22:23], 0, v[6:7]
	global_load_dword v11, v[8:9], off
	s_mov_b32 s22, 6
	s_ashr_i32 s23, s22, 31
	s_lshl_b64 s[22:23], s[22:23], 3
	s_add_u32 s22, s0, s22
	s_addc_u32 s23, s1, s23
	s_load_dwordx2 s[22:23], s[22:23], 0x0
	v_cndmask_b32_e32 v5, v240, v5, vcc
	v_lshlrev_b32_e32 v5, 2, v5
	s_mov_b32 s40, 21
	s_mov_b32 s38, 21
	s_waitcnt lgkmcnt(0)
	v_lshl_add_u64 v[8:9], s[22:23], 0, v[6:7]
	s_mov_b32 s22, 7
	global_load_dword v13, v[8:9], off
	s_ashr_i32 s23, s22, 31
	s_lshl_b64 s[22:23], s[22:23], 3
	s_add_u32 s22, s0, s22
	s_addc_u32 s23, s1, s23
	s_load_dwordx2 s[22:23], s[22:23], 0x0
	s_ashr_i32 s20, s20, 5
	s_and_b32 s20, s20, -2
	s_mov_b32 s36, 21
	s_waitcnt lgkmcnt(0)
	v_lshl_add_u64 v[6:7], s[22:23], 0, v[6:7]
	global_load_dword v14, v[6:7], off
	s_and_b32 s22, s2, 7
	s_lshl_b32 s22, s22, 3
	s_bfe_u32 s23, s2, 0x30003
	s_add_i32 s22, s22, s23
	s_mulk_i32 s22, 0x600
	s_lshr_b32 s23, s2, 6
	s_lshl_b32 s23, s23, 4
	s_add_i32 s22, s22, s23
	s_add_i32 s20, s20, s22
	s_waitcnt vmcnt(0)
	v_mul_f32_e32 v12, v0, v11
	ds_bpermute_b32 v7, v5, v12
	s_waitcnt lgkmcnt(0)
	v_fmac_f32_e32 v7, v0, v11
	v_xor_b32_e32 v0, 2, v240
	v_cmp_lt_i32_e32 vcc, v0, v16
	s_waitcnt vmcnt(0)
	v_mul_f32_e32 v15, v13, v14
	v_cndmask_b32_e32 v0, v240, v0, vcc
	v_lshlrev_b32_e32 v6, 2, v0
	ds_bpermute_b32 v0, v6, v7
	s_waitcnt lgkmcnt(0)
	v_add_f32_e32 v0, v7, v0
	v_xor_b32_e32 v7, 4, v240
	v_cmp_lt_i32_e32 vcc, v7, v16
	s_nop 1
	v_cndmask_b32_e32 v7, v240, v7, vcc
	v_lshlrev_b32_e32 v7, 2, v7
	ds_bpermute_b32 v8, v7, v0
	s_waitcnt lgkmcnt(0)
	v_add_f32_e32 v0, v0, v8
	v_xor_b32_e32 v8, 8, v240
	v_cmp_lt_i32_e32 vcc, v8, v16
	s_nop 1
	v_cndmask_b32_e32 v8, v240, v8, vcc
	v_lshlrev_b32_e32 v8, 2, v8
	ds_bpermute_b32 v9, v8, v0
	s_waitcnt lgkmcnt(0)
	v_add_f32_e32 v0, v0, v9
	v_xor_b32_e32 v9, 16, v240
	v_cmp_lt_i32_e32 vcc, v9, v16
	s_nop 1
	v_cndmask_b32_e32 v9, v240, v9, vcc
	v_lshlrev_b32_e32 v9, 2, v9
	ds_bpermute_b32 v11, v9, v0
	s_waitcnt lgkmcnt(0)
	v_add_f32_e32 v0, v0, v11
	v_xor_b32_e32 v11, 32, v240
	v_cmp_lt_i32_e32 vcc, v11, v16
	s_nop 1
	v_cndmask_b32_e32 v11, v240, v11, vcc
	v_lshlrev_b32_e32 v11, 2, v11
	ds_bpermute_b32 v12, v11, v0
	s_waitcnt lgkmcnt(0)
	v_add_f32_e32 v0, v0, v12
	v_mul_f32_e32 v12, 0x3fb8aa3b, v0
	v_fma_f32 v16, v0, s26, -v12
	v_rndne_f32_e32 v17, v12
	v_fmac_f32_e32 v16, 0x32a5705f, v0
	v_sub_f32_e32 v12, v12, v17
	v_add_f32_e32 v12, v12, v16
	v_exp_f32_e32 v12, v12
	v_cvt_i32_f32_e32 v16, v17
	v_cmp_ngt_f32_e32 vcc, s27, v0
	v_ldexp_f32 v12, v12, v16
	s_nop 0
	v_cndmask_b32_e32 v12, 0, v12, vcc
	v_cmp_nlt_f32_e32 vcc, s34, v0
	s_nop 1
	v_cndmask_b32_e32 v0, v18, v12, vcc
	ds_bpermute_b32 v12, v5, v15
	s_waitcnt lgkmcnt(0)
	v_fmac_f32_e32 v12, v13, v14
	ds_bpermute_b32 v13, v6, v12
	s_waitcnt lgkmcnt(0)
	v_add_f32_e32 v12, v12, v13
	ds_bpermute_b32 v13, v7, v12
	s_waitcnt lgkmcnt(0)
	v_add_f32_e32 v12, v12, v13
	ds_bpermute_b32 v13, v8, v12
	s_waitcnt lgkmcnt(0)
	v_add_f32_e32 v12, v12, v13
	ds_bpermute_b32 v13, v9, v12
	s_waitcnt lgkmcnt(0)
	v_add_f32_e32 v12, v12, v13
	ds_bpermute_b32 v11, v11, v12
	s_waitcnt lgkmcnt(0)
	v_add_f32_e32 v11, v12, v11
	v_mul_f32_e32 v12, 0x3fb8aa3b, v11
	v_fma_f32 v13, v11, s26, -v12
	v_rndne_f32_e32 v14, v12
	v_fmac_f32_e32 v13, 0x32a5705f, v11
	v_sub_f32_e32 v12, v12, v14
	v_add_f32_e32 v12, v12, v13
	v_exp_f32_e32 v12, v12
	v_cvt_i32_f32_e32 v13, v14
	v_cmp_ngt_f32_e32 vcc, s27, v11
	v_ldexp_f32 v12, v12, v13
	s_nop 0
	v_cndmask_b32_e32 v12, 0, v12, vcc
	v_cmp_nlt_f32_e32 vcc, s34, v11
	s_mov_b32 s34, 8
	s_nop 0
	v_cndmask_b32_e32 v11, v18, v12, vcc
	v_sub_f32_e32 v0, v0, v11
	v_add_f32_e32 v0, v10, v0
	s_nop 0
	v_readfirstlane_b32 s26, v0
	v_bfe_u32 v0, v4, 5, 1
	v_or_b32_e32 v10, s20, v0
	s_mov_b32 s20, 0x18000
	v_cmp_gt_i32_e32 vcc, s20, v10
	s_and_saveexec_b64 s[42:43], vcc
	s_cbranch_execz .LBB0_502
	s_ashr_i32 s41, s40, 31
	s_lshl_b64 s[22:23], s[40:41], 3
	s_add_u32 s22, s0, s22
	s_addc_u32 s23, s1, s23
	s_load_dwordx2 s[22:23], s[22:23], 0x0
	v_mul_f32_e32 v0, 0x3f19999a, v2
	v_readlane_b32 s20, v255, 30
	s_mulk_i32 s20, 0x300
	v_add_f32_e32 v0, 0xbf4ccccd, v0
	s_waitcnt lgkmcnt(0)
	s_add_u32 s40, s22, 0x2d600000
	s_addc_u32 s41, s23, 0
	s_ashr_i32 s39, s38, 31
	s_lshl_b64 s[22:23], s[38:39], 3
	s_add_u32 s22, s0, s22
	s_addc_u32 s23, s1, s23
	s_load_dwordx2 s[22:23], s[22:23], 0x0
	v_add_f32_e32 v11, 1.0, v0
	v_lshlrev_b32_e32 v0, 2, v3
	v_and_b32_e32 v12, 0x7c, v0
	v_lshlrev_b32_e32 v0, 2, v12
	s_waitcnt lgkmcnt(0)
	s_add_u32 s44, s22, 0x35600000
	s_addc_u32 s45, s23, 0
	s_ashr_i32 s35, s34, 31
	s_lshl_b64 s[22:23], s[34:35], 3
	s_add_u32 s22, s0, s22
	s_addc_u32 s23, s1, s23
	s_ashr_i32 s37, s36, 31
	s_load_dwordx2 s[22:23], s[22:23], 0x0
	s_lshl_b64 s[34:35], s[36:37], 3
	s_add_u32 s34, s0, s34
	s_addc_u32 s35, s1, s35
	s_load_dwordx2 s[34:35], s[34:35], 0x0
	s_lshl_b64 s[36:37], s[20:21], 2
	s_waitcnt lgkmcnt(0)
	s_add_u32 s22, s22, s36
	s_addc_u32 s23, s23, s37
	s_mov_b32 s27, s26
	s_mov_b32 s20, s26
	v_lshl_add_u64 v[2:3], s[22:23], 0, v[0:1]
	v_lshlrev_b32_e32 v4, 7, v10
	s_mov_b64 s[36:37], 0
	v_lshlrev_b32_e32 v0, 1, v12
	s_xor_b32 s46, s26, 0x80000000
; __device__ __forceinline__ unsigned pk2(float lo, float hi) { return pg8::cvt_pk_bf16(lo, hi); }
; __device__ __forceinline__ void diff_final(const bfu* D0, const bfu* D1, float lam, const float* sg, float omli, bfu* CAT, int gw, int NGW, int lane) {
;     const int half = lane >> 5, l32 = lane & 31;
;     for (int it = gw * 2 + half; it < M * 6; it += NGW * 2) { const int row = it / 6, h = it - row * 6;
;         const v2u a_ = __builtin_nontemporal_load((const v2u*)(D0 + (size_t)row * 768 + h * 128 + l32 * 4)), b_ = __builtin_nontemporal_load((const v2u*)(D1 + (size_t)row * 768 + h * 128 + l32 * 4));
;         const f32x4 v = (f32x4){bflo(a_.x), bfhi(a_.x), bflo(a_.y), bfhi(a_.y)} - (f32x4){bflo(b_.x), bfhi(b_.x), bflo(b_.y), bfhi(b_.y)} * lam; float s = (v.x * v.x + v.y * v.y) + (v.z * v.z + v.w * v.w);
; #pragma unroll
;         for (int o = 1; o < 32; o <<= 1) s += __shfl_xor(s, o);
;         const float r = omli / sqrtf(s * (1.f / 128.f) + EPS); const f32x4 g4 = *(const f32x4*)(sg + h * 128 + l32 * 4);
;         v2u w; w.x = pk2(v.x * r * g4.x, v.y * r * g4.y); w.y = pk2(v.z * r * g4.z, v.w * r * g4.w); *(v2u*)(CAT + (size_t)row * DM + 768 + h * 128 + l32 * 4) = w; }
; }
.LBB0_501:
	s_mov_b32 s22, 0x2aaaaaab
	v_mul_hi_i32 v16, v10, s22
	v_lshrrev_b32_e32 v17, 31, v16
	v_mov_b64_e32 v[12:13], s[40:41]
	v_add_u32_e32 v16, v16, v17
	v_mad_i64_i32 v[12:13], s[22:23], v16, s66, v[12:13]
	s_movk_i32 s22, 0xfd00
	s_nop 0
	v_mad_u64_u32 v[18:19], s[22:23], v16, s22, v[4:5]
	v_ashrrev_i32_e32 v19, 31, v18
	v_mov_b64_e32 v[14:15], s[44:45]
	v_lshlrev_b64 v[20:21], 1, v[18:19]
	v_mad_i64_i32 v[14:15], s[22:23], v16, s66, v[14:15]
	v_lshl_add_u64 v[12:13], v[12:13], 0, v[20:21]
	v_lshl_add_u64 v[14:15], v[14:15], 0, v[20:21]
	v_lshl_add_u64 v[12:13], v[12:13], 0, v[0:1]
	v_lshl_add_u64 v[14:15], v[14:15], 0, v[0:1]
	global_load_dwordx2 v[22:23], v[12:13], off nt
	global_load_dwordx2 v[24:25], v[14:15], off nt
	v_ashrrev_i32_e32 v17, 31, v16
	v_lshlrev_b64 v[12:13], 12, v[16:17]
	v_lshl_add_u64 v[14:15], v[18:19], 2, v[2:3]
	v_lshl_add_u64 v[16:17], s[34:35], 0, v[12:13]
	global_load_dwordx4 v[12:15], v[14:15], off
	s_xor_b32 s47, s20, 0x80000000
	v_lshl_add_u64 v[16:17], v[16:17], 0, v[20:21]
	v_add_u32_e32 v10, 0x40, v10
	s_and_b32 s22, s2, 7
	s_lshl_b32 s22, s22, 3
	s_bfe_u32 s23, s2, 0x30003
	s_add_i32 s22, s22, s23
	s_mulk_i32 s22, 0x600
	s_addk_i32 s22, 0x5ff
	v_cmp_lt_i32_e32 vcc, s22, v10
	s_or_b64 s[36:37], vcc, s[36:37]
	v_lshl_add_u64 v[16:17], v[16:17], 0, v[0:1]
	v_add_u32_e32 v4, 0x2000, v4
	s_waitcnt vmcnt(2)
	v_lshlrev_b32_e32 v18, 16, v22
	v_and_b32_e32 v19, 0xffff0000, v22
	v_lshlrev_b32_e32 v20, 16, v23
	v_and_b32_e32 v21, 0xffff0000, v23
	s_waitcnt vmcnt(1)
	v_lshlrev_b32_e32 v22, 16, v24
	v_and_b32_e32 v23, 0xffff0000, v24
	v_lshlrev_b32_e32 v24, 16, v25
	v_and_b32_e32 v25, 0xffff0000, v25
	v_pk_fma_f32 v[18:19], s[26:27], v[22:23], v[18:19] neg_lo:[1,0,0] neg_hi:[1,0,0]
	v_pk_fma_f32 v[20:21], s[46:47], v[24:25], v[20:21]
	v_pk_mul_f32 v[24:25], v[18:19], v[18:19]
	v_pk_mul_f32 v[22:23], v[20:21], v[20:21]
	s_nop 0
	v_pk_mov_b32 v[26:27], v[24:25], v[22:23] op_sel:[1,0]
	v_mov_b32_e32 v25, v23
	v_pk_add_f32 v[22:23], v[26:27], v[24:25]
	s_nop 0
	v_add_f32_e32 v22, v22, v23
	s_waitcnt lgkmcnt(0)
	s_nop 1
	v_add_f32_dpp v22, v22, v22 quad_perm:[1,0,3,2] row_mask:0xf bank_mask:0xf
	s_nop 1
	v_add_f32_dpp v22, v22, v22 quad_perm:[2,3,0,1] row_mask:0xf bank_mask:0xf
	s_nop 1
	v_add_f32_dpp v22, v22, v22 row_half_mirror row_mask:0xf bank_mask:0xf
	s_nop 1
	v_add_f32_dpp v22, v22, v22 row_mirror row_mask:0xf bank_mask:0xf
	v_mov_b32_e32 v23, v22
	s_nop 1
	v_permlane16_swap_b32_e32 v22, v23
	v_add_f32_e32 v22, v22, v23
	v_fmamk_f32 v22, v22, 0x3c000000, v236
	v_mul_f32_e32 v23, 0x4f800000, v22
	v_cmp_gt_f32_e32 vcc, s68, v22
	s_nop 1
	v_cndmask_b32_e32 v22, v22, v23, vcc
	v_sqrt_f32_e32 v23, v22
	s_nop 0
	v_add_u32_e32 v24, -1, v23
	v_add_u32_e32 v25, 1, v23
	v_fma_f32 v26, -v24, v23, v22
	v_fma_f32 v27, -v25, v23, v22
	v_cmp_ge_f32_e64 s[38:39], 0, v26
	s_nop 1
	v_cndmask_b32_e64 v23, v23, v24, s[38:39]
	v_cmp_lt_f32_e64 s[38:39], 0, v27
	s_nop 1
	v_cndmask_b32_e64 v23, v23, v25, s[38:39]
	v_mul_f32_e32 v24, 0x37800000, v23
	v_cndmask_b32_e32 v23, v23, v24, vcc
	v_cmp_class_f32_e32 vcc, v22, v234
	s_nop 1
	v_cndmask_b32_e32 v22, v23, v22, vcc
	v_div_scale_f32 v23, s[22:23], v22, v22, v11
	v_rcp_f32_e32 v25, v23
	v_div_scale_f32 v24, vcc, v11, v22, v11
	v_fma_f32 v26, -v23, v25, 1.0
	v_fmac_f32_e32 v25, v26, v25
	v_mul_f32_e32 v26, v24, v25
	v_fma_f32 v27, -v23, v26, v24
	v_fmac_f32_e32 v26, v27, v25
	v_fma_f32 v23, -v23, v26, v24
	v_div_fmas_f32 v23, v23, v25, v26
	v_div_fixup_f32 v22, v23, v22, v11
	v_pk_mul_f32 v[18:19], v[18:19], v[22:23] op_sel_hi:[1,0]
	v_pk_mul_f32 v[20:21], v[20:21], v[22:23] op_sel_hi:[1,0]
	v_add_co_u32_e32 v16, vcc, 0x29600000, v16
	s_waitcnt vmcnt(0)
	v_pk_mul_f32 v[12:13], v[12:13], v[18:19]
	v_pk_mul_f32 v[14:15], v[14:15], v[20:21]
	v_addc_co_u32_e32 v17, vcc, 0, v17, vcc
	v_cvt_pk_bf16_f32 v12, v12, v13
	v_cvt_pk_bf16_f32 v13, v14, v15
	global_store_dwordx2 v[16:17], v[12:13], off offset:1536
	s_andn2_b64 exec, exec, s[36:37]
	s_cbranch_execnz .LBB0_501

; __device__ __forceinline__ unsigned xb_ld(unsigned* p)              { return __hip_atomic_load(p, __ATOMIC_RELAXED, __HIP_MEMORY_SCOPE_AGENT); }
; __device__ __forceinline__ unsigned xb_add(unsigned* p, unsigned v) { return __hip_atomic_fetch_add(p, v, __ATOMIC_RELAXED, __HIP_MEMORY_SCOPE_AGENT); }
; #define XB_SPIN(cond, bar) do { unsigned _sp = 0; while (cond) { __builtin_amdgcn_s_sleep(1); \
;     if ((++_sp & 255u) == 0u) { if (xb_ld(&(bar)[XB_TMO])) break; if (_sp > XB_SPIN_CAP) { atomicAdd(&(bar)[XB_TMO], 1u); break; } } } } while (0)
; __device__ __forceinline__ void xcd_barrier(const XcdBarrier& b) {
;     asm volatile("s_waitcnt vmcnt(0)" ::: "memory");
;     __syncthreads();
;     if (threadIdx.x == 0) {
;         unsigned* bar = b.bar;
;         __builtin_amdgcn_s_waitcnt(0);
;         unsigned nloc = b.st[0], nx = b.st[1];
;         if (nloc == 0u) { xcd_barrier_complete(bar, b.x, nloc, nx); b.st[0] = nloc; b.st[1] = nx; }
;         const unsigned old = xb_add(&bar[XB_XSUB(b.x)], 1u);
;         const unsigned gen = old / nloc;
;         if (old + 1u == (gen + 1u) * nloc) {
;             __builtin_amdgcn_fence(__ATOMIC_RELEASE, "agent");
;             asm volatile("s_waitcnt vmcnt(0)" ::: "memory");
;             const unsigned og = xb_add(&bar[XB_TOP], 1u);
;             const unsigned tg = og / nx;
;             if (og + 1u == (tg + 1u) * nx) xb_add(&bar[XB_TOPGEN], 1u);
;             else XB_SPIN(xb_ld(&bar[XB_TOPGEN]) == tg, bar);
;             __builtin_amdgcn_fence(__ATOMIC_ACQUIRE, "agent");
;             xb_add(&bar[XB_XGEN(b.x)], 1u);
;             asm volatile("s_waitcnt vmcnt(0)" ::: "memory");
;         } else {
;             XB_SPIN(xb_ld(&bar[XB_XGEN(b.x)]) == gen, bar);
;             __builtin_amdgcn_fence(__ATOMIC_ACQUIRE, "agent");
;             asm volatile("s_waitcnt vmcnt(0)" ::: "memory");
;         }
.LBB0_503:
	v_readlane_b32 s20, v255, 24
	s_add_i32 s20, s20, 3
	s_cmp_lt_i32 s20, s59
	s_cselect_b64 s[26:27], -1, 0
	s_and_b64 s[4:5], s[4:5], s[26:27]
	s_andn2_b64 vcc, exec, s[4:5]
	s_cbranch_vccnz .LBB0_557
	s_waitcnt vmcnt(0)
	s_barrier
	s_and_saveexec_b64 s[4:5], s[74:75]
	s_cbranch_execz .LBB0_556
	s_cmp_lg_u32 s100, 0
	s_cbranch_scc1 .Lgs_known_15533
	v_readlane_b32 s22, v255, 6
	v_readlane_b32 s23, v255, 7
	s_nop 4
	global_load_dword v6, v1, s[22:23] offset:1024 sc1
	global_load_dword v7, v1, s[22:23] offset:1088 sc1
	global_load_dword v8, v1, s[22:23] offset:1152 sc1
	global_load_dword v9, v1, s[22:23] offset:1216 sc1
	global_load_dword v10, v1, s[22:23] offset:1280 sc1
	global_load_dword v11, v1, s[22:23] offset:1344 sc1
	global_load_dword v12, v1, s[22:23] offset:1408 sc1
	global_load_dword v13, v1, s[22:23] offset:1472 sc1
	s_waitcnt vmcnt(0)
	v_add_u32_e32 v14, -1, v6
	v_and_b32_e32 v14, v14, v6
	v_add_u32_e32 v15, -1, v7
	v_and_b32_e32 v15, v15, v7
	v_or_b32_e32 v14, v14, v15
	v_add_u32_e32 v15, -1, v8
	v_and_b32_e32 v15, v15, v8
	v_or_b32_e32 v14, v14, v15
	v_add_u32_e32 v15, -1, v9
	v_and_b32_e32 v15, v15, v9
	v_or_b32_e32 v14, v14, v15
	v_add_u32_e32 v15, -1, v10
	v_and_b32_e32 v15, v15, v10
	v_or_b32_e32 v14, v14, v15
	v_add_u32_e32 v15, -1, v11
	v_and_b32_e32 v15, v15, v11
	v_or_b32_e32 v14, v14, v15
	v_add_u32_e32 v15, -1, v12
	v_and_b32_e32 v15, v15, v12
	v_or_b32_e32 v14, v14, v15
	v_add_u32_e32 v15, -1, v13
	v_and_b32_e32 v15, v15, v13
	v_or_b32_e32 v14, v14, v15
	s_nop 0
	v_readfirstlane_b32 s22, v14
	s_cmp_eq_u32 s22, 0
	s_cselect_b32 s100, 1, 2
.Lgs_known_15533:
	s_cmp_eq_u32 s100, 1
	s_cbranch_scc0 .Lgs_full_15533
	s_waitcnt vmcnt(0) lgkmcnt(0)
	v_readlane_b32 s22, v255, 6
	v_readlane_b32 s23, v255, 7
	s_and_b32 s36, s2, 7
	s_lshl_b32 s36, s36, 3
	s_bfe_u32 s37, s2, 0x30003
	s_add_i32 s36, s36, s37
	s_lshl_b32 s36, s36, 6
	s_addk_i32 s36, 0x800
	v_mov_b32_e32 v6, s36
	v_mov_b32_e32 v7, 1
	s_add_i32 s101, s101, 4
	global_atomic_add v6, v7, s[22:23]
	s_mov_b32 s36, 0
.Lgs_spin_15533:
	global_load_dword v8, v6, s[22:23] sc1
	s_waitcnt vmcnt(0)
	v_readfirstlane_b32 s37, v8
	s_sub_i32 s37, s37, s101
	s_cmp_ge_i32 s37, 0
	s_cbranch_scc1 .Lgs_done_15533
	s_sleep 1
	s_add_i32 s36, s36, 1
	s_cmp_lt_u32 s36, 0x100000
	s_cbranch_scc1 .Lgs_spin_15533
.Lgs_done_15533:
	buffer_inv sc1
	s_waitcnt vmcnt(0)
	s_branch .LBB0_556
.Lgs_full_15533:
	v_readlane_b32 s22, v255, 27
	s_waitcnt vmcnt(0) expcnt(0) lgkmcnt(0)
	s_nop 0
	v_mov_b32_e32 v0, s22
	ds_read_b32 v3, v0
	v_readlane_b32 s22, v255, 28
	s_waitcnt lgkmcnt(0)
	v_cmp_ne_u32_e32 vcc, 0, v3
	v_mov_b32_e32 v0, s22
	ds_read_b32 v2, v0
	s_cbranch_vccnz .LBB0_520
	v_readlane_b32 s34, v254, 0
	v_readlane_b32 s35, v254, 1
	s_load_dwordx2 s[22:23], s[34:35], 0x4
	s_waitcnt lgkmcnt(0)
	s_mul_i32 s22, s22, s3
	s_mul_i32 s22, s22, s23
	s_mov_b32 s23, 1
	s_branch .LBB0_508

; __device__ __forceinline__ void xcd_barrier(const XcdBarrier& b) {
;     asm volatile("s_waitcnt vmcnt(0)" ::: "memory");
;     __syncthreads();
;     if (threadIdx.x == 0) {
;         unsigned* bar = b.bar;
;         __builtin_amdgcn_s_waitcnt(0);
;         unsigned nloc = b.st[0], nx = b.st[1];
;         if (nloc == 0u) { xcd_barrier_complete(bar, b.x, nloc, nx); b.st[0] = nloc; b.st[1] = nx; }
.LBB0_578:
	v_readlane_b32 s20, v255, 24
	s_add_i32 s20, s20, 4
	s_waitcnt lgkmcnt(0)
	s_cmp_lt_i32 s20, s59
	s_cselect_b64 s[26:27], -1, 0
	s_and_b64 s[4:5], s[4:5], s[26:27]
	s_andn2_b64 vcc, exec, s[4:5]
	s_cbranch_vccnz .LBB0_632
	s_waitcnt vmcnt(0)
	s_waitcnt vmcnt(0)
	s_barrier
	s_and_saveexec_b64 s[4:5], s[74:75]
	s_cbranch_execz .LBB0_631
	s_cmp_lg_u32 s100, 0
	s_cbranch_scc1 .Lgs_known_17063
	v_readlane_b32 s22, v255, 6
	v_readlane_b32 s23, v255, 7
	s_nop 4
	global_load_dword v6, v1, s[22:23] offset:1024 sc1
	global_load_dword v7, v1, s[22:23] offset:1088 sc1
	global_load_dword v8, v1, s[22:23] offset:1152 sc1
	global_load_dword v9, v1, s[22:23] offset:1216 sc1
	global_load_dword v10, v1, s[22:23] offset:1280 sc1
	global_load_dword v11, v1, s[22:23] offset:1344 sc1
	global_load_dword v12, v1, s[22:23] offset:1408 sc1
	global_load_dword v13, v1, s[22:23] offset:1472 sc1
	s_waitcnt vmcnt(0)
	v_add_u32_e32 v14, -1, v6
	v_and_b32_e32 v14, v14, v6
	v_add_u32_e32 v15, -1, v7
	v_and_b32_e32 v15, v15, v7
	v_or_b32_e32 v14, v14, v15
	v_add_u32_e32 v15, -1, v8
	v_and_b32_e32 v15, v15, v8
	v_or_b32_e32 v14, v14, v15
	v_add_u32_e32 v15, -1, v9
	v_and_b32_e32 v15, v15, v9
	v_or_b32_e32 v14, v14, v15
	v_add_u32_e32 v15, -1, v10
	v_and_b32_e32 v15, v15, v10
	v_or_b32_e32 v14, v14, v15
	v_add_u32_e32 v15, -1, v11
	v_and_b32_e32 v15, v15, v11
	v_or_b32_e32 v14, v14, v15
	v_add_u32_e32 v15, -1, v12
	v_and_b32_e32 v15, v15, v12
	v_or_b32_e32 v14, v14, v15
	v_add_u32_e32 v15, -1, v13
	v_and_b32_e32 v15, v15, v13
	v_or_b32_e32 v14, v14, v15
	s_nop 0
	v_readfirstlane_b32 s22, v14
	s_cmp_eq_u32 s22, 0
	s_cselect_b32 s100, 1, 2

; template <bool FINAL, bool DUMMY = false> __device__ __forceinline__ void norm_rows(const bfu* F, bfu* XB, const float* g1, float* RS, float* xout, int gw, int NGW, int lane, bfu* dummy = nullptr) {
;     int m = gw; if (m >= M) return;
;     v4u fw[4], xw[4];
; #pragma unroll
;     for (int j = 0; j < 4; ++j) { fw[j] = __builtin_nontemporal_load((const v4u*)(F + (size_t)m * DM) + lane + 64 * j); xw[j] = ((const v4u*)(XB + (size_t)m * DM) + lane)[64 * j]; }
;     for (; m < M; m += NGW) {
;         f32x4 f[8], x[8]; float s = 0.f;
; #pragma unroll
;         for (int j = 0; j < 4; ++j) {
;             f[2 * j] = (f32x4){bflo(fw[j].x), bfhi(fw[j].x), bflo(fw[j].y), bfhi(fw[j].y)}; f[2 * j + 1] = (f32x4){bflo(fw[j].z), bfhi(fw[j].z), bflo(fw[j].w), bfhi(fw[j].w)};
;             x[2 * j] = (f32x4){bflo(xw[j].x), bfhi(xw[j].x), bflo(xw[j].y), bfhi(xw[j].y)}; x[2 * j + 1] = (f32x4){bflo(xw[j].z), bfhi(xw[j].z), bflo(xw[j].w), bfhi(xw[j].w)}; }
;         const int mn = m + NGW;
;         if (mn < M) {
; #pragma unroll
;             for (int j = 0; j < 4; ++j) { fw[j] = __builtin_nontemporal_load((const v4u*)(F + (size_t)mn * DM) + lane + 64 * j); xw[j] = ((const v4u*)(XB + (size_t)mn * DM) + lane)[64 * j]; }
;         }
; #pragma unroll
;         for (int k = 0; k < 8; ++k) s += (f[k].x * f[k].x + f[k].y * f[k].y) + (f[k].z * f[k].z + f[k].w * f[k].w);
;         const float rstd1 = 1.f / sqrtf(wave_sum(s) * (1.f / DM) + EPS);
;         float s2 = 0.f;
; #pragma unroll
;         for (int k = 0; k < 8; ++k) { const f32x4 gg = ((const f32x4*)g1)[2 * lane + 128 * (k >> 1) + (k & 1)]; x[k] = x[k] + f[k] * rstd1 * gg; s2 += (x[k].x * x[k].x + x[k].y * x[k].y) + (x[k].z * x[k].z + x[k].w * x[k].w); }
.LBB0_632:
	s_cmp_le_i32 s58, s20
	s_cselect_b64 s[4:5], -1, 0
	s_and_b64 s[22:23], s[4:5], s[26:27]
	s_andn2_b64 vcc, exec, s[22:23]
	s_cbranch_vccnz .LBB0_640
	v_mov_b32_e32 v0, v232
	s_mov_b32 s42, 21
	v_readfirstlane_b32 s20, v0
	s_ashr_i32 s22, s20, 6
	s_and_b32 s20, s2, 7
	s_lshl_b32 s20, s20, 11
	s_bfe_u32 s27, s2, 0x30003
	s_lshl_b32 s27, s27, 8
	s_add_i32 s20, s20, s27
	s_lshr_b32 s27, s2, 6
	s_lshl_b32 s27, s27, 3
	s_add_i32 s20, s20, s27
	s_add_i32 s26, s22, s20
	s_mov_b32 s40, 21
	s_mov_b32 s36, 14
	s_mov_b32 s34, 21
	s_cmpk_gt_i32 s26, 0x3fff
	s_cbranch_scc1 .LBB0_640
	s_ashr_i32 s43, s42, 31
	s_lshl_b64 s[42:43], s[42:43], 3
	s_add_u32 s42, s0, s42
	s_addc_u32 s43, s1, s43
	s_ashr_i32 s41, s40, 31
	s_lshl_b64 s[40:41], s[40:41], 3
	s_add_u32 s40, s0, s40
	s_addc_u32 s41, s1, s41
	s_ashr_i32 s37, s36, 31
	s_lshl_b64 s[36:37], s[36:37], 3
	s_add_u32 s36, s0, s36
	s_addc_u32 s37, s1, s37
	s_ashr_i32 s35, s34, 31
	s_lshl_b64 s[34:35], s[34:35], 3
	s_add_u32 s44, s0, s34
	s_addc_u32 s45, s1, s35
	s_load_dwordx2 s[34:35], s[42:43], 0x0
	s_nop 0
	s_load_dwordx2 s[36:37], s[36:37], 0x0
	s_nop 0
	s_load_dwordx2 s[44:45], s[44:45], 0x0
	s_nop 0
	s_load_dwordx2 s[42:43], s[40:41], 0x0
	v_readlane_b32 s20, v255, 30
	s_lshl_b32 s20, s20, 11
	s_lshl_b64 s[40:41], s[20:21], 2
	s_waitcnt lgkmcnt(0)
	s_add_u32 s46, s36, s40
	s_addc_u32 s47, s37, s41
	s_ashr_i32 s27, s26, 31
	s_lshl_b64 s[40:41], s[26:27], 12
	v_and_b32_e32 v10, 63, v0
	s_add_u32 s36, s42, s40
	v_lshlrev_b32_e32 v0, 4, v10
	s_addc_u32 s37, s43, s41
	v_lshl_add_u64 v[2:3], s[36:37], 0, v[0:1]
	s_mov_b64 s[48:49], 0x18e00000
	s_add_u32 s40, s34, s40
	s_mov_b32 s20, 0x18e00000
	v_lshl_add_u64 v[4:5], v[2:3], 0, s[48:49]
	s_addc_u32 s41, s35, s41
	v_add_co_u32_e32 v2, vcc, s20, v2
	v_lshl_add_u64 v[6:7], s[40:41], 0, v[0:1]
	s_nop 0
	v_addc_co_u32_e32 v3, vcc, 0, v3, vcc
	s_mov_b32 s20, 0x2d600000
	global_load_dwordx4 v[34:37], v[4:5], off offset:3072
	global_load_dwordx4 v[42:45], v[4:5], off offset:2048
	global_load_dwordx4 v[50:53], v[4:5], off offset:1024
	global_load_dwordx4 v[54:57], v[2:3], off
	v_add_co_u32_e32 v2, vcc, s20, v6
	s_mov_b64 s[40:41], 0x2d600000
	s_nop 0
	v_addc_co_u32_e32 v3, vcc, 0, v7, vcc
	v_lshl_add_u64 v[8:9], v[6:7], 0, s[40:41]
	global_load_dwordx4 v[62:65], v[2:3], off nt
	global_load_dwordx4 v[58:61], v[8:9], off offset:1024 nt
	global_load_dwordx4 v[46:49], v[8:9], off offset:2048 nt
	global_load_dwordx4 v[38:41], v[8:9], off offset:3072 nt
	v_and_b32_e32 v2, 64, v240
	v_mov_b32_e32 v3, v1
	v_add_u32_e32 v11, 64, v2
	v_lshlrev_b32_e32 v2, 5, v10
	v_lshl_add_u64 v[66:67], s[46:47], 0, v[2:3]
	s_mov_b64 s[46:47], 0x1000
	v_lshl_add_u64 v[68:69], v[66:67], 0, s[46:47]
	s_mov_b64 s[46:47], 0x1800
	v_lshl_add_u64 v[70:71], v[66:67], 0, s[46:47]
	global_load_dwordx4 v[128:131], v[66:67], off offset:16
	global_load_dwordx4 v[132:135], v[66:67], off
	global_load_dwordx4 v[136:139], v[66:67], off offset:2064
	global_load_dwordx4 v[140:143], v[66:67], off offset:2048
	global_load_dwordx4 v[144:147], v[68:69], off offset:16
	global_load_dwordx4 v[148:151], v[68:69], off
	global_load_dwordx4 v[152:155], v[70:71], off offset:16
	global_load_dwordx4 v[156:159], v[70:71], off
	s_waitcnt vmcnt(0)
	s_lshl_b64 s[46:47], s[26:27], 2
	v_xor_b32_e32 v4, 1, v240
	s_add_u32 s20, s44, s46
	v_xor_b32_e32 v5, 2, v240
	v_cmp_lt_i32_e32 vcc, v4, v11
	s_addc_u32 s23, s45, s47
	v_xor_b32_e32 v6, 4, v240
	v_cndmask_b32_e32 v4, v240, v4, vcc
	v_cmp_lt_i32_e32 vcc, v5, v11
	s_add_u32 s44, s20, 0x1c0000
	v_xor_b32_e32 v7, 8, v240
	v_cndmask_b32_e32 v5, v240, v5, vcc
	v_cmp_lt_i32_e32 vcc, v6, v11
	s_addc_u32 s45, s23, 0
	s_sub_i32 s20, s26, s22
	s_addk_i32 s20, 0x20
	s_and_b32 s26, s26, 0x7ff
	s_add_i32 s22, s20, s22
	v_xor_b32_e32 v8, 16, v240
	v_cndmask_b32_e32 v6, v240, v6, vcc
	v_cmp_lt_i32_e32 vcc, v7, v11
	s_ashr_i32 s23, s22, 31
	v_xor_b32_e32 v9, 32, v240
	v_cndmask_b32_e32 v7, v240, v7, vcc
	v_cmp_lt_i32_e32 vcc, v8, v11
	s_lshl_b64 s[22:23], s[22:23], 12
	s_add_u32 s46, s34, s22
	v_cndmask_b32_e32 v8, v240, v8, vcc
	v_cmp_lt_i32_e32 vcc, v9, v11
	s_addc_u32 s47, s35, s23
	v_cmp_eq_u32_e64 s[40:41], 0, v10
	v_cndmask_b32_e32 v9, v240, v9, vcc
	v_lshlrev_b32_e32 v116, 2, v4
	v_lshlrev_b32_e32 v117, 2, v5
	v_lshlrev_b32_e32 v118, 2, v6
	v_lshlrev_b32_e32 v119, 2, v7
	v_lshlrev_b32_e32 v120, 2, v8
	v_lshlrev_b32_e32 v121, 2, v9
	s_add_u32 s50, s42, s22
	s_addc_u32 s51, s43, s23
	s_waitcnt vmcnt(0)
	v_mov_b64_e32 v[18:19], v[42:43]
	v_mov_b64_e32 v[10:11], v[50:51]
	v_mov_b64_e32 v[2:3], v[54:55]
	v_mov_b64_e32 v[22:23], v[34:35]
	v_mov_b64_e32 v[4:5], v[56:57]
	v_mov_b64_e32 v[12:13], v[52:53]
	v_mov_b64_e32 v[6:7], v[62:63]
	v_mov_b64_e32 v[14:15], v[58:59]
	v_mov_b64_e32 v[26:27], v[46:47]
	v_mov_b64_e32 v[30:31], v[38:39]
	v_mov_b64_e32 v[20:21], v[44:45]
	v_mov_b64_e32 v[24:25], v[36:37]
	v_mov_b64_e32 v[8:9], v[64:65]
	v_mov_b64_e32 v[16:17], v[60:61]
	v_mov_b64_e32 v[28:29], v[48:49]
	v_mov_b64_e32 v[32:33], v[40:41]
	s_branch .LBB0_636
.LBB0_635:
	s_or_b64 exec, exec, s[34:35]
	s_movk_i32 s22, 0x80
	s_mov_b32 s23, 0
	s_add_u32 s44, s44, s22
	s_addc_u32 s45, s45, s23
	s_add_u32 s36, s36, 0x20000
	s_addc_u32 s37, s37, 0
	s_add_u32 s46, s46, 0x20000
	s_addc_u32 s47, s47, 0
	s_add_u32 s50, s50, 0x20000
	v_mov_b64_e32 v[56:57], v[4:5]
	v_mov_b64_e32 v[52:53], v[12:13]
	v_mov_b64_e32 v[44:45], v[20:21]
	s_waitcnt lgkmcnt(0)
	v_mov_b64_e32 v[36:37], v[24:25]
	v_mov_b64_e32 v[64:65], v[8:9]
	v_mov_b64_e32 v[60:61], v[16:17]
	v_mov_b64_e32 v[48:49], v[28:29]
	v_mov_b64_e32 v[40:41], v[32:33]
	s_addc_u32 s51, s51, 0
	s_andn2_b64 vcc, exec, s[52:53]
	v_mov_b64_e32 v[54:55], v[2:3]
	v_mov_b64_e32 v[50:51], v[10:11]
	v_mov_b64_e32 v[42:43], v[18:19]
	v_mov_b64_e32 v[34:35], v[22:23]
	v_mov_b64_e32 v[62:63], v[6:7]
	v_mov_b64_e32 v[58:59], v[14:15]
	v_mov_b64_e32 v[46:47], v[26:27]
	v_mov_b64_e32 v[38:39], v[30:31]
	s_cbranch_vccz .LBB0_640

; __device__ __forceinline__ void xcd_barrier(const XcdBarrier& b) {
;     asm volatile("s_waitcnt vmcnt(0)" ::: "memory");
;     __syncthreads();
;     if (threadIdx.x == 0) {
;         unsigned* bar = b.bar;
;         __builtin_amdgcn_s_waitcnt(0);
;         unsigned nloc = b.st[0], nx = b.st[1];
;         if (nloc == 0u) { xcd_barrier_complete(bar, b.x, nloc, nx); b.st[0] = nloc; b.st[1] = nx; }
.LBB0_640:
	v_readlane_b32 s20, v255, 24
	s_add_i32 s20, s20, 5
	s_cmp_lt_i32 s20, s59
	s_cselect_b64 s[26:27], -1, 0
	s_and_b64 s[4:5], s[4:5], s[26:27]
	s_andn2_b64 vcc, exec, s[4:5]
	s_cbranch_vccnz .LBB0_694
	s_waitcnt vmcnt(0)
	s_waitcnt vmcnt(0)
	s_barrier
	s_and_saveexec_b64 s[4:5], s[74:75]
	s_cbranch_execz .LBB0_693
	s_cmp_lg_u32 s100, 0
	s_cbranch_scc1 .Lgs_known_18221
	v_readlane_b32 s22, v255, 6
	v_readlane_b32 s23, v255, 7
	s_nop 4
	global_load_dword v6, v1, s[22:23] offset:1024 sc1
	global_load_dword v7, v1, s[22:23] offset:1088 sc1
	global_load_dword v8, v1, s[22:23] offset:1152 sc1
	global_load_dword v9, v1, s[22:23] offset:1216 sc1
	global_load_dword v10, v1, s[22:23] offset:1280 sc1
	global_load_dword v11, v1, s[22:23] offset:1344 sc1
	global_load_dword v12, v1, s[22:23] offset:1408 sc1
	global_load_dword v13, v1, s[22:23] offset:1472 sc1
	s_waitcnt vmcnt(0)
	v_add_u32_e32 v14, -1, v6
	v_and_b32_e32 v14, v14, v6
	v_add_u32_e32 v15, -1, v7
	v_and_b32_e32 v15, v15, v7
	v_or_b32_e32 v14, v14, v15
	v_add_u32_e32 v15, -1, v8
	v_and_b32_e32 v15, v15, v8
	v_or_b32_e32 v14, v14, v15
	v_add_u32_e32 v15, -1, v9
	v_and_b32_e32 v15, v15, v9
	v_or_b32_e32 v14, v14, v15
	v_add_u32_e32 v15, -1, v10
	v_and_b32_e32 v15, v15, v10
	v_or_b32_e32 v14, v14, v15
	v_add_u32_e32 v15, -1, v11
	v_and_b32_e32 v15, v15, v11
	v_or_b32_e32 v14, v14, v15
	v_add_u32_e32 v15, -1, v12
	v_and_b32_e32 v15, v15, v12
	v_or_b32_e32 v14, v14, v15
	v_add_u32_e32 v15, -1, v13
	v_and_b32_e32 v15, v15, v13
	v_or_b32_e32 v14, v14, v15
	s_nop 0
	v_readfirstlane_b32 s22, v14
	s_cmp_eq_u32 s22, 0
	s_cselect_b32 s100, 1, 2

; __device__ __forceinline__ void xcd_barrier(const XcdBarrier& b) {
;     asm volatile("s_waitcnt vmcnt(0)" ::: "memory");
;     __syncthreads();
;     if (threadIdx.x == 0) {
;         unsigned* bar = b.bar;
;         __builtin_amdgcn_s_waitcnt(0);
;         unsigned nloc = b.st[0], nx = b.st[1];
;         if (nloc == 0u) { xcd_barrier_complete(bar, b.x, nloc, nx); b.st[0] = nloc; b.st[1] = nx; }
.LBB0_711:
	v_readlane_b32 s20, v255, 24
	s_add_i32 s20, s20, 6
	s_waitcnt lgkmcnt(0)
	s_cmp_lt_i32 s20, s59
	s_cselect_b64 s[26:27], -1, 0
	s_and_b64 s[4:5], s[4:5], s[26:27]
	s_andn2_b64 vcc, exec, s[4:5]
	s_cbranch_vccnz .LBB0_765
	s_waitcnt vmcnt(0)
	s_waitcnt vmcnt(0)
	s_barrier
	s_and_saveexec_b64 s[4:5], s[74:75]
	s_cbranch_execz .LBB0_764
	s_cmp_lg_u32 s100, 0
	s_cbranch_scc1 .Lgs_known_20220
	v_readlane_b32 s22, v255, 6
	v_readlane_b32 s23, v255, 7
	s_nop 4
	global_load_dword v6, v1, s[22:23] offset:1024 sc1
	global_load_dword v7, v1, s[22:23] offset:1088 sc1
	global_load_dword v8, v1, s[22:23] offset:1152 sc1
	global_load_dword v9, v1, s[22:23] offset:1216 sc1
	global_load_dword v10, v1, s[22:23] offset:1280 sc1
	global_load_dword v11, v1, s[22:23] offset:1344 sc1
	global_load_dword v12, v1, s[22:23] offset:1408 sc1
	global_load_dword v13, v1, s[22:23] offset:1472 sc1
	s_waitcnt vmcnt(0)
	v_add_u32_e32 v14, -1, v6
	v_and_b32_e32 v14, v14, v6
	v_add_u32_e32 v15, -1, v7
	v_and_b32_e32 v15, v15, v7
	v_or_b32_e32 v14, v14, v15
	v_add_u32_e32 v15, -1, v8
	v_and_b32_e32 v15, v15, v8
	v_or_b32_e32 v14, v14, v15
	v_add_u32_e32 v15, -1, v9
	v_and_b32_e32 v15, v15, v9
	v_or_b32_e32 v14, v14, v15
	v_add_u32_e32 v15, -1, v10
	v_and_b32_e32 v15, v15, v10
	v_or_b32_e32 v14, v14, v15
	v_add_u32_e32 v15, -1, v11
	v_and_b32_e32 v15, v15, v11
	v_or_b32_e32 v14, v14, v15
	v_add_u32_e32 v15, -1, v12
	v_and_b32_e32 v15, v15, v12
	v_or_b32_e32 v14, v14, v15
	v_add_u32_e32 v15, -1, v13
	v_and_b32_e32 v15, v15, v13
	v_or_b32_e32 v14, v14, v15
	s_nop 0
	v_readfirstlane_b32 s22, v14
	s_cmp_eq_u32 s22, 0
	s_cselect_b32 s100, 1, 2

; __device__ __forceinline__ unsigned xb_add(unsigned* p, unsigned v) { return __hip_atomic_fetch_add(p, v, __ATOMIC_RELAXED, __HIP_MEMORY_SCOPE_AGENT); }
; __device__ __forceinline__ void xcd_barrier(const XcdBarrier& b) {
;     asm volatile("s_waitcnt vmcnt(0)" ::: "memory");
;     __syncthreads();
;     if (threadIdx.x == 0) {
;         unsigned* bar = b.bar;
;         __builtin_amdgcn_s_waitcnt(0);
;         unsigned nloc = b.st[0], nx = b.st[1];
;         if (nloc == 0u) { xcd_barrier_complete(bar, b.x, nloc, nx); b.st[0] = nloc; b.st[1] = nx; }
;         const unsigned old = xb_add(&bar[XB_XSUB(b.x)], 1u);
.LBB0_790:
	v_readlane_b32 s20, v255, 24
	s_add_i32 s20, s20, 7
	s_waitcnt lgkmcnt(0)
	s_cmp_lt_i32 s20, s59
	s_cselect_b64 s[26:27], -1, 0
	s_and_b64 s[4:5], s[4:5], s[26:27]
	s_andn2_b64 vcc, exec, s[4:5]
	s_cbranch_vccnz .LBB0_844
	s_waitcnt vmcnt(0)
	s_waitcnt vmcnt(0)
	s_barrier
	s_and_saveexec_b64 s[4:5], s[74:75]
	s_cbranch_execz .LBB0_843
	s_cmp_lg_u32 s100, 0
	s_cbranch_scc1 .Lgs_known_21762
	v_readlane_b32 s22, v255, 6
	v_readlane_b32 s23, v255, 7
	s_nop 4
	global_load_dword v6, v1, s[22:23] offset:1024 sc1
	global_load_dword v7, v1, s[22:23] offset:1088 sc1
	global_load_dword v8, v1, s[22:23] offset:1152 sc1
	global_load_dword v9, v1, s[22:23] offset:1216 sc1
	global_load_dword v10, v1, s[22:23] offset:1280 sc1
	global_load_dword v11, v1, s[22:23] offset:1344 sc1
	global_load_dword v12, v1, s[22:23] offset:1408 sc1
	global_load_dword v13, v1, s[22:23] offset:1472 sc1
	s_waitcnt vmcnt(0)
	v_add_u32_e32 v14, -1, v6
	v_and_b32_e32 v14, v14, v6
	v_add_u32_e32 v15, -1, v7
	v_and_b32_e32 v15, v15, v7
	v_or_b32_e32 v14, v14, v15
	v_add_u32_e32 v15, -1, v8
	v_and_b32_e32 v15, v15, v8
	v_or_b32_e32 v14, v14, v15
	v_add_u32_e32 v15, -1, v9
	v_and_b32_e32 v15, v15, v9
	v_or_b32_e32 v14, v14, v15
	v_add_u32_e32 v15, -1, v10
	v_and_b32_e32 v15, v15, v10
	v_or_b32_e32 v14, v14, v15
	v_add_u32_e32 v15, -1, v11
	v_and_b32_e32 v15, v15, v11
	v_or_b32_e32 v14, v14, v15
	v_add_u32_e32 v15, -1, v12
	v_and_b32_e32 v15, v15, v12
	v_or_b32_e32 v14, v14, v15
	v_add_u32_e32 v15, -1, v13
	v_and_b32_e32 v15, v15, v13
	v_or_b32_e32 v14, v14, v15
	s_nop 0
	v_readfirstlane_b32 s22, v14
	s_cmp_eq_u32 s22, 0
	s_cselect_b32 s100, 1, 2
.Lgs_known_21762:
	s_cmp_eq_u32 s100, 1
	s_cbranch_scc0 .Lgs_full_21762
	v_readlane_b32 s22, v255, 30
	s_cmp_eq_u32 s22, 3
	s_cbranch_scc1 .Lgs_full_21762
	s_waitcnt vmcnt(0) lgkmcnt(0)
	v_readlane_b32 s22, v255, 6
	v_readlane_b32 s23, v255, 7
	s_and_b32 s36, s2, 7
	s_lshl_b32 s36, s36, 3
	s_bfe_u32 s37, s2, 0x30003
	s_add_i32 s36, s36, s37
	s_lshl_b32 s36, s36, 6
	s_addk_i32 s36, 0x800
	v_mov_b32_e32 v6, s36
	v_mov_b32_e32 v7, 1
	s_add_i32 s101, s101, 4
	global_atomic_add v6, v7, s[22:23]
	s_mov_b32 s36, 0

; template <bool FINAL, bool DUMMY = false> __device__ __forceinline__ void norm_rows(const bfu* F, bfu* XB, const float* g1, float* RS, float* xout, int gw, int NGW, int lane, bfu* dummy = nullptr) {
;     int m = gw; if (m >= M) return;
;     v4u fw[4], xw[4];
; #pragma unroll
;     for (int j = 0; j < 4; ++j) { fw[j] = __builtin_nontemporal_load((const v4u*)(F + (size_t)m * DM) + lane + 64 * j); xw[j] = ((const v4u*)(XB + (size_t)m * DM) + lane)[64 * j]; }
;     for (; m < M; m += NGW) {
;         f32x4 f[8], x[8]; float s = 0.f;
; #pragma unroll
;         for (int j = 0; j < 4; ++j) {
;             f[2 * j] = (f32x4){bflo(fw[j].x), bfhi(fw[j].x), bflo(fw[j].y), bfhi(fw[j].y)}; f[2 * j + 1] = (f32x4){bflo(fw[j].z), bfhi(fw[j].z), bflo(fw[j].w), bfhi(fw[j].w)};
;             x[2 * j] = (f32x4){bflo(xw[j].x), bfhi(xw[j].x), bflo(xw[j].y), bfhi(xw[j].y)}; x[2 * j + 1] = (f32x4){bflo(xw[j].z), bfhi(xw[j].z), bflo(xw[j].w), bfhi(xw[j].w)}; }
;         const int mn = m + NGW;
;         if (mn < M) {
; #pragma unroll
;             for (int j = 0; j < 4; ++j) { fw[j] = __builtin_nontemporal_load((const v4u*)(F + (size_t)mn * DM) + lane + 64 * j); xw[j] = ((const v4u*)(XB + (size_t)mn * DM) + lane)[64 * j]; }
;         }
; #pragma unroll
;         for (int k = 0; k < 8; ++k) s += (f[k].x * f[k].x + f[k].y * f[k].y) + (f[k].z * f[k].z + f[k].w * f[k].w);
;         const float rstd1 = 1.f / sqrtf(wave_sum(s) * (1.f / DM) + EPS);
;         float s2 = 0.f;
; #pragma unroll
;         for (int k = 0; k < 8; ++k) { const f32x4 gg = ((const f32x4*)g1)[2 * lane + 128 * (k >> 1) + (k & 1)]; x[k] = x[k] + f[k] * rstd1 * gg; s2 += (x[k].x * x[k].x + x[k].y * x[k].y) + (x[k].z * x[k].z + x[k].w * x[k].w); }
.LBB0_844:
	s_cmp_le_i32 s58, s20
	s_cselect_b64 s[4:5], -1, 0
	s_and_b64 s[22:23], s[4:5], s[26:27]
	s_andn2_b64 vcc, exec, s[22:23]
	s_cbranch_vccnz .LBB0_860
	v_mov_b32_e32 v0, v232
	s_mov_b64 s[34:35], -1
	v_readfirstlane_b32 s20, v0
	s_ashr_i32 s48, s20, 6
	s_and_b32 s20, s2, 7
	s_lshl_b32 s20, s20, 11
	s_bfe_u32 s27, s2, 0x30003
	s_lshl_b32 s27, s27, 8
	s_add_i32 s20, s20, s27
	s_lshr_b32 s27, s2, 6
	s_lshl_b32 s27, s27, 3
	s_add_i32 s20, s20, s27
	s_add_i32 s26, s48, s20
	v_readlane_b32 s20, v255, 30
	s_cmp_eq_u32 s20, 3
	v_and_b32_e32 v116, 63, v0
	s_cbranch_scc1 .LBB0_854
	s_mov_b32 s34, 21
	s_mov_b32 s40, 21
	s_mov_b32 s38, 19
	s_mov_b32 s36, 21
	s_cmpk_gt_i32 s26, 0x3fff
	s_cbranch_scc1 .LBB0_853
	s_ashr_i32 s35, s34, 31
	s_lshl_b64 s[22:23], s[34:35], 3
	s_add_u32 s22, s0, s22
	s_addc_u32 s23, s1, s23
	s_ashr_i32 s41, s40, 31
	s_load_dwordx2 s[34:35], s[22:23], 0x0
	s_lshl_b64 s[22:23], s[40:41], 3
	s_add_u32 s22, s0, s22
	s_addc_u32 s23, s1, s23
	s_ashr_i32 s39, s38, 31
	s_load_dwordx2 s[40:41], s[22:23], 0x0
	s_lshl_b64 s[22:23], s[38:39], 3
	s_add_u32 s22, s0, s22
	s_addc_u32 s23, s1, s23
	s_load_dwordx2 s[22:23], s[22:23], 0x0
	s_ashr_i32 s37, s36, 31
	s_lshl_b64 s[36:37], s[36:37], 3
	s_add_u32 s36, s0, s36
	v_readlane_b32 s20, v255, 30
	s_addc_u32 s37, s1, s37
	s_lshl_b32 s20, s20, 11
	s_load_dwordx2 s[42:43], s[36:37], 0x0
	s_lshl_b64 s[36:37], s[20:21], 2
	s_waitcnt lgkmcnt(0)
	s_add_u32 s44, s22, s36
	s_addc_u32 s45, s23, s37
	s_ashr_i32 s27, s26, 31
	s_lshl_b64 s[22:23], s[26:27], 12
	s_add_u32 s36, s40, s22
	s_addc_u32 s37, s41, s23
	v_lshlrev_b32_e32 v0, 4, v116
	s_add_u32 s22, s34, s22
	v_lshl_add_u64 v[2:3], s[36:37], 0, v[0:1]
	s_mov_b64 s[38:39], 0x18e00000
	s_addc_u32 s23, s35, s23
	s_mov_b32 s20, 0x18e00000
	v_lshl_add_u64 v[4:5], v[2:3], 0, s[38:39]
	v_lshl_add_u64 v[6:7], s[22:23], 0, v[0:1]
	s_mov_b64 s[22:23], 0x2d600000
	v_add_co_u32_e32 v2, vcc, s20, v2
	v_lshl_add_u64 v[8:9], v[6:7], 0, s[22:23]
	s_nop 0
	v_addc_co_u32_e32 v3, vcc, 0, v3, vcc
	s_mov_b32 s20, 0x2d600000
	global_load_dwordx4 v[34:37], v[4:5], off offset:3072
	global_load_dwordx4 v[38:41], v[8:9], off offset:3072 nt
	global_load_dwordx4 v[42:45], v[4:5], off offset:2048
	global_load_dwordx4 v[46:49], v[8:9], off offset:2048 nt
	global_load_dwordx4 v[50:53], v[4:5], off offset:1024
	global_load_dwordx4 v[54:57], v[8:9], off offset:1024 nt
	global_load_dwordx4 v[58:61], v[2:3], off
	v_add_co_u32_e32 v2, vcc, s20, v6
	s_mov_b64 s[22:23], 0x1000
	s_nop 0
	v_addc_co_u32_e32 v3, vcc, 0, v7, vcc
	global_load_dwordx4 v[62:65], v[2:3], off nt
	v_and_b32_e32 v2, 64, v240
	v_add_u32_e32 v2, 64, v2
	v_xor_b32_e32 v3, 1, v240
	v_cmp_lt_i32_e32 vcc, v3, v2
	v_cmp_eq_u32_e64 s[38:39], 0, v116
	s_waitcnt vmcnt(0)
	v_mov_b64_e32 v[30:31], v[38:39]
	v_cndmask_b32_e32 v3, v240, v3, vcc
	v_lshlrev_b32_e32 v117, 2, v3
	v_xor_b32_e32 v3, 2, v240
	v_cmp_lt_i32_e32 vcc, v3, v2
	v_mov_b64_e32 v[10:11], v[50:51]
	v_mov_b64_e32 v[18:19], v[42:43]
	v_cndmask_b32_e32 v3, v240, v3, vcc
	v_lshlrev_b32_e32 v118, 2, v3
	v_xor_b32_e32 v3, 4, v240
	v_cmp_lt_i32_e32 vcc, v3, v2
	v_mov_b64_e32 v[22:23], v[34:35]
	v_mov_b64_e32 v[6:7], v[62:63]
	v_cndmask_b32_e32 v3, v240, v3, vcc
	v_lshlrev_b32_e32 v119, 2, v3
	v_xor_b32_e32 v3, 8, v240
	v_cmp_lt_i32_e32 vcc, v3, v2
	v_mov_b64_e32 v[14:15], v[54:55]
	v_mov_b64_e32 v[26:27], v[46:47]
	v_cndmask_b32_e32 v3, v240, v3, vcc
	v_lshlrev_b32_e32 v120, 2, v3
	v_xor_b32_e32 v3, 16, v240
	v_cmp_lt_i32_e32 vcc, v3, v2
	v_mov_b64_e32 v[12:13], v[52:53]
	v_mov_b64_e32 v[20:21], v[44:45]
	v_cndmask_b32_e32 v3, v240, v3, vcc
	v_lshlrev_b32_e32 v121, 2, v3
	v_xor_b32_e32 v3, 32, v240
	v_cmp_lt_i32_e32 vcc, v3, v2
	v_mov_b64_e32 v[24:25], v[36:37]
	v_mov_b64_e32 v[8:9], v[64:65]
	v_cndmask_b32_e32 v2, v240, v3, vcc
	v_lshlrev_b32_e32 v122, 2, v2
	v_lshlrev_b32_e32 v2, 5, v116
	v_mov_b32_e32 v3, v1
	v_lshl_add_u64 v[66:67], s[44:45], 0, v[2:3]
	v_lshl_add_u64 v[68:69], v[66:67], 0, s[22:23]
	s_mov_b64 s[22:23], 0x1800
	v_lshl_add_u64 v[70:71], v[66:67], 0, s[22:23]
	global_load_dwordx4 v[128:131], v[66:67], off offset:16
	global_load_dwordx4 v[132:135], v[66:67], off
	global_load_dwordx4 v[136:139], v[66:67], off offset:2064
	global_load_dwordx4 v[140:143], v[66:67], off offset:2048
	global_load_dwordx4 v[144:147], v[68:69], off offset:16
	global_load_dwordx4 v[148:151], v[68:69], off
	global_load_dwordx4 v[152:155], v[70:71], off offset:16
	global_load_dwordx4 v[156:159], v[70:71], off
	s_waitcnt vmcnt(0)
	s_lshl_b64 s[22:23], s[26:27], 2
	s_add_u32 s20, s42, s22
	s_addc_u32 s22, s43, s23
	s_add_u32 s42, s20, 0x1c0000
	s_addc_u32 s43, s22, 0
	s_sub_i32 s20, s26, s48
	s_addk_i32 s20, 0x20
	s_add_i32 s22, s20, s48
	s_ashr_i32 s23, s22, 31
	s_lshl_b64 s[22:23], s[22:23], 12
	s_add_u32 s44, s34, s22
	s_addc_u32 s45, s35, s23
	s_add_u32 s46, s40, s22
	v_mov_b64_e32 v[2:3], v[58:59]
	s_addc_u32 s47, s41, s23
	s_and_b32 s20, s26, 0x7ff
	v_mov_b64_e32 v[4:5], v[60:61]
	v_mov_b64_e32 v[16:17], v[56:57]
	v_mov_b64_e32 v[28:29], v[48:49]
	v_mov_b64_e32 v[32:33], v[40:41]
	s_branch .LBB0_849
.LBB0_848:
	s_or_b64 exec, exec, s[34:35]
	s_movk_i32 s22, 0x80
	s_mov_b32 s23, 0
	s_add_u32 s42, s42, s22
	s_addc_u32 s43, s43, s23
	s_add_u32 s36, s36, 0x20000
	s_addc_u32 s37, s37, 0
	s_add_u32 s44, s44, 0x20000
	s_addc_u32 s45, s45, 0
	s_add_u32 s46, s46, 0x20000
	v_mov_b64_e32 v[60:61], v[4:5]
	v_mov_b64_e32 v[52:53], v[12:13]
	v_mov_b64_e32 v[44:45], v[20:21]
	s_waitcnt lgkmcnt(0)
	v_mov_b64_e32 v[36:37], v[24:25]
	v_mov_b64_e32 v[64:65], v[8:9]
	v_mov_b64_e32 v[56:57], v[16:17]
	v_mov_b64_e32 v[48:49], v[28:29]
	v_mov_b64_e32 v[40:41], v[32:33]
	s_addc_u32 s47, s47, 0
	s_and_b64 vcc, exec, s[50:51]
	v_mov_b64_e32 v[58:59], v[2:3]
	v_mov_b64_e32 v[50:51], v[10:11]
	v_mov_b64_e32 v[42:43], v[18:19]
	v_mov_b64_e32 v[34:35], v[22:23]
	v_mov_b64_e32 v[62:63], v[6:7]
	v_mov_b64_e32 v[54:55], v[14:15]
	v_mov_b64_e32 v[46:47], v[26:27]
	v_mov_b64_e32 v[38:39], v[30:31]
	s_cbranch_vccnz .LBB0_853

; __device__ __forceinline__ void xcd_barrier(const XcdBarrier& b) {
;     asm volatile("s_waitcnt vmcnt(0)" ::: "memory");
;     __syncthreads();
;     if (threadIdx.x == 0) {
;         unsigned* bar = b.bar;
;         __builtin_amdgcn_s_waitcnt(0);
;         unsigned nloc = b.st[0], nx = b.st[1];
;         if (nloc == 0u) { xcd_barrier_complete(bar, b.x, nloc, nx); b.st[0] = nloc; b.st[1] = nx; }
.LBB0_860:
	v_readlane_b32 s20, v255, 24
	s_add_i32 s20, s20, 8
	s_cmp_lt_i32 s20, s59
	s_cselect_b64 s[22:23], -1, 0
	s_and_b64 s[4:5], s[4:5], s[22:23]
	v_writelane_b32 v255, s20, 24
	s_andn2_b64 vcc, exec, s[4:5]
	s_cbranch_vccnz .LBB0_127
	s_waitcnt vmcnt(0)
	s_waitcnt vmcnt(0)
	s_barrier
	s_and_saveexec_b64 s[4:5], s[74:75]
	s_cbranch_execz .LBB0_126
	s_cmp_lg_u32 s100, 0
	s_cbranch_scc1 .Lgs_known_23337
	v_readlane_b32 s22, v255, 6
	v_readlane_b32 s23, v255, 7
	s_nop 4
	global_load_dword v6, v1, s[22:23] offset:1024 sc1
	global_load_dword v7, v1, s[22:23] offset:1088 sc1
	global_load_dword v8, v1, s[22:23] offset:1152 sc1
	global_load_dword v9, v1, s[22:23] offset:1216 sc1
	global_load_dword v10, v1, s[22:23] offset:1280 sc1
	global_load_dword v11, v1, s[22:23] offset:1344 sc1
	global_load_dword v12, v1, s[22:23] offset:1408 sc1
	global_load_dword v13, v1, s[22:23] offset:1472 sc1
	s_waitcnt vmcnt(0)
	v_add_u32_e32 v14, -1, v6
	v_and_b32_e32 v14, v14, v6
	v_add_u32_e32 v15, -1, v7
	v_and_b32_e32 v15, v15, v7
	v_or_b32_e32 v14, v14, v15
	v_add_u32_e32 v15, -1, v8
	v_and_b32_e32 v15, v15, v8
	v_or_b32_e32 v14, v14, v15
	v_add_u32_e32 v15, -1, v9
	v_and_b32_e32 v15, v15, v9
	v_or_b32_e32 v14, v14, v15
	v_add_u32_e32 v15, -1, v10
	v_and_b32_e32 v15, v15, v10
	v_or_b32_e32 v14, v14, v15
	v_add_u32_e32 v15, -1, v11
	v_and_b32_e32 v15, v15, v11
	v_or_b32_e32 v14, v14, v15
	v_add_u32_e32 v15, -1, v12
	v_and_b32_e32 v15, v15, v12
	v_or_b32_e32 v14, v14, v15
	v_add_u32_e32 v15, -1, v13
	v_and_b32_e32 v15, v15, v13
	v_or_b32_e32 v14, v14, v15
	s_nop 0
	v_readfirstlane_b32 s22, v14
	s_cmp_eq_u32 s22, 0
	s_cselect_b32 s100, 1, 2

; __device__ __forceinline__ void xcd_barrier(const XcdBarrier& b) {
;     asm volatile("s_waitcnt vmcnt(0)" ::: "memory");
;     __syncthreads();
;     if (threadIdx.x == 0) {
;         unsigned* bar = b.bar;
;         __builtin_amdgcn_s_waitcnt(0);
;         unsigned nloc = b.st[0], nx = b.st[1];
;         if (nloc == 0u) { xcd_barrier_complete(bar, b.x, nloc, nx); b.st[0] = nloc; b.st[1] = nx; }
.Lgs_full_23337:
	v_readlane_b32 s20, v255, 27
	s_waitcnt vmcnt(0) expcnt(0) lgkmcnt(0)
	s_nop 0
	v_mov_b32_e32 v0, s20
	ds_read_b32 v3, v0
	v_readlane_b32 s20, v255, 28
	s_waitcnt lgkmcnt(0)
	v_cmp_ne_u32_e32 vcc, 0, v3
	v_mov_b32_e32 v0, s20
	ds_read_b32 v2, v0
	s_cbranch_vccnz .LBB0_877
	v_readlane_b32 s26, v254, 0
	v_readlane_b32 s27, v254, 1
	s_load_dwordx2 s[22:23], s[26:27], 0x4
	s_waitcnt lgkmcnt(0)
	s_mul_i32 s20, s22, s3
	s_mul_i32 s20, s20, s23
	s_mov_b32 s22, 1
	s_branch .LBB0_865
